# no-op scalar fillers (satisfied s_waitcnt lgkmcnt, setprio 0/1 pairs) removed from the steady-loop MFMA blocks, on top of v45
# speedup vs baseline: 1.0070x; 1.0070x over previous
.LBB0_233:
	ds_read_b128 v[130:133], v213
	ds_read_b128 v[134:137], v214
	ds_read_b128 v[138:141], v215
	ds_read_b128 v[142:145], v216
	ds_read_b128 v[146:149], v217
	ds_read_b128 v[150:153], v218
	ds_read_b128 v[154:157], v219
	ds_read_b128 v[158:161], v220
	s_add_i32 s4, s33, 0xffffe080
	s_cmp_eq_u32 s58, 12
	s_cselect_b32 s61, s18, s4
	s_cselect_b32 s60, s19, s57
	s_add_i32 s59, s61, 0x80
	s_mov_b32 s4, s70
	s_mov_b32 m0, s38
	ds_read_b128 v[162:165], v221
	ds_read_b128 v[166:169], v221 offset:2048
	ds_read_b128 v[170:173], v222
	ds_read_b128 v[174:177], v222 offset:2048
	ds_read_b128 v[178:181], v221 offset:4096
	ds_read_b128 v[182:185], v221 offset:6144
	ds_read_b128 v[186:189], v222 offset:4096
	ds_read_b128 v[190:193], v222 offset:6144
	buffer_load_dwordx4 v207, s[4:7], s33 offen lds
	s_mov_b32 m0, s41
	s_nop 0
	buffer_load_dwordx4 v209, s[4:7], s33 offen lds
	s_waitcnt vmcnt(8)
	s_waitcnt lgkmcnt(0)
	s_barrier
	s_setprio 1
	v_mfma_f32_16x16x32_bf16 v[114:117], v[130:133], v[162:165], v[114:117]
	v_mfma_f32_16x16x32_bf16 v[110:113], v[138:141], v[162:165], v[110:113]
	v_mfma_f32_16x16x32_bf16 v[106:109], v[130:133], v[166:169], v[106:109]
	v_mfma_f32_16x16x32_bf16 v[102:105], v[138:141], v[166:169], v[102:105]
	v_mfma_f32_16x16x32_bf16 v[98:101], v[130:133], v[178:181], v[98:101]
	v_mfma_f32_16x16x32_bf16 v[94:97], v[138:141], v[178:181], v[94:97]
	v_mfma_f32_16x16x32_bf16 v[90:93], v[130:133], v[182:185], v[90:93]
	v_mfma_f32_16x16x32_bf16 v[86:89], v[138:141], v[182:185], v[86:89]
	v_mfma_f32_16x16x32_bf16 v[114:117], v[134:137], v[170:173], v[114:117]
	v_mfma_f32_16x16x32_bf16 v[110:113], v[142:145], v[170:173], v[110:113]
	v_mfma_f32_16x16x32_bf16 v[106:109], v[134:137], v[174:177], v[106:109]
	v_mfma_f32_16x16x32_bf16 v[102:105], v[142:145], v[174:177], v[102:105]
	v_mfma_f32_16x16x32_bf16 v[98:101], v[134:137], v[186:189], v[98:101]
	v_mfma_f32_16x16x32_bf16 v[94:97], v[142:145], v[186:189], v[94:97]
	v_mfma_f32_16x16x32_bf16 v[90:93], v[134:137], v[190:193], v[90:93]
	v_mfma_f32_16x16x32_bf16 v[86:89], v[142:145], v[190:193], v[86:89]
	v_mfma_f32_16x16x32_bf16 v[82:85], v[146:149], v[162:165], v[82:85]
	v_mfma_f32_16x16x32_bf16 v[74:77], v[154:157], v[162:165], v[74:77]
	v_mfma_f32_16x16x32_bf16 v[70:73], v[146:149], v[166:169], v[70:73]
	v_mfma_f32_16x16x32_bf16 v[66:69], v[154:157], v[166:169], v[66:69]
	v_mfma_f32_16x16x32_bf16 v[62:65], v[146:149], v[178:181], v[62:65]
	v_mfma_f32_16x16x32_bf16 v[58:61], v[154:157], v[178:181], v[58:61]
	v_mfma_f32_16x16x32_bf16 v[54:57], v[146:149], v[182:185], v[54:57]
	v_mfma_f32_16x16x32_bf16 v[50:53], v[154:157], v[182:185], v[50:53]
	v_mfma_f32_16x16x32_bf16 v[82:85], v[150:153], v[170:173], v[82:85]
	v_mfma_f32_16x16x32_bf16 v[74:77], v[158:161], v[170:173], v[74:77]
	v_mfma_f32_16x16x32_bf16 v[70:73], v[150:153], v[174:177], v[70:73]
	v_mfma_f32_16x16x32_bf16 v[66:69], v[158:161], v[174:177], v[66:69]
	v_mfma_f32_16x16x32_bf16 v[62:65], v[150:153], v[186:189], v[62:65]
	v_mfma_f32_16x16x32_bf16 v[58:61], v[158:161], v[186:189], v[58:61]
	v_mfma_f32_16x16x32_bf16 v[54:57], v[150:153], v[190:193], v[54:57]
	v_mfma_f32_16x16x32_bf16 v[50:53], v[158:161], v[190:193], v[50:53]
	s_setprio 0
	s_barrier
	s_mov_b32 m0, s21
	ds_read_b128 v[162:165], v221 offset:16384
	ds_read_b128 v[166:169], v221 offset:18432
	ds_read_b128 v[170:173], v222 offset:16384
	ds_read_b128 v[174:177], v222 offset:18432
	ds_read_b128 v[178:181], v221 offset:20480
	ds_read_b128 v[182:185], v221 offset:22528
	ds_read_b128 v[186:189], v222 offset:20480
	ds_read_b128 v[190:193], v222 offset:22528
	buffer_load_dwordx4 v208, s[4:7], s60 offen lds
	s_mov_b32 m0, s22
	s_add_i32 s62, s60, 0x40000
	buffer_load_dwordx4 v210, s[4:7], s60 offen lds
	s_mov_b32 m0, s23
	s_nop 0
	buffer_load_dwordx4 v208, s[4:7], s62 offen lds
	s_mov_b32 m0, s24
	s_nop 0
	buffer_load_dwordx4 v210, s[4:7], s62 offen lds
	s_mov_b32 m0, s20
	s_nop 0
	buffer_load_dwordx4 v207, s[4:7], s61 offen lds
	s_mov_b32 m0, s25
	s_nop 0
	buffer_load_dwordx4 v209, s[4:7], s61 offen lds
	s_waitcnt vmcnt(8)
	s_waitcnt lgkmcnt(0)
	s_barrier
	s_setprio 1
	v_mfma_f32_16x16x32_bf16 v[78:81], v[130:133], v[162:165], v[78:81]
	v_mfma_f32_16x16x32_bf16 v[46:49], v[138:141], v[162:165], v[46:49]
	v_mfma_f32_16x16x32_bf16 v[42:45], v[130:133], v[166:169], v[42:45]
	v_mfma_f32_16x16x32_bf16 v[38:41], v[138:141], v[166:169], v[38:41]
	v_mfma_f32_16x16x32_bf16 v[34:37], v[130:133], v[178:181], v[34:37]
	v_mfma_f32_16x16x32_bf16 v[30:33], v[138:141], v[178:181], v[30:33]
	v_mfma_f32_16x16x32_bf16 v[26:29], v[130:133], v[182:185], v[26:29]
	v_mfma_f32_16x16x32_bf16 v[22:25], v[138:141], v[182:185], v[22:25]
	v_mfma_f32_16x16x32_bf16 v[78:81], v[134:137], v[170:173], v[78:81]
	v_mfma_f32_16x16x32_bf16 v[46:49], v[142:145], v[170:173], v[46:49]
	v_mfma_f32_16x16x32_bf16 v[42:45], v[134:137], v[174:177], v[42:45]
	v_mfma_f32_16x16x32_bf16 v[38:41], v[142:145], v[174:177], v[38:41]
	v_mfma_f32_16x16x32_bf16 v[34:37], v[134:137], v[186:189], v[34:37]
	v_mfma_f32_16x16x32_bf16 v[30:33], v[142:145], v[186:189], v[30:33]
	v_mfma_f32_16x16x32_bf16 v[26:29], v[134:137], v[190:193], v[26:29]
	v_mfma_f32_16x16x32_bf16 v[22:25], v[142:145], v[190:193], v[22:25]
	v_mfma_f32_16x16x32_bf16 v[18:21], v[146:149], v[162:165], v[18:21]
	v_mfma_f32_16x16x32_bf16 v[14:17], v[154:157], v[162:165], v[14:17]
	v_mfma_f32_16x16x32_bf16 v[10:13], v[146:149], v[166:169], v[10:13]
	v_mfma_f32_16x16x32_bf16 v[6:9], v[154:157], v[166:169], v[6:9]
	v_mfma_f32_16x16x32_bf16 v[2:5], v[146:149], v[178:181], v[2:5]
	v_mfma_f32_16x16x32_bf16 v[126:129], v[154:157], v[178:181], v[126:129]
	v_mfma_f32_16x16x32_bf16 v[122:125], v[146:149], v[182:185], v[122:125]
	v_mfma_f32_16x16x32_bf16 v[118:121], v[154:157], v[182:185], v[118:121]
	v_mfma_f32_16x16x32_bf16 v[18:21], v[150:153], v[170:173], v[18:21]
	v_mfma_f32_16x16x32_bf16 v[14:17], v[158:161], v[170:173], v[14:17]
	v_mfma_f32_16x16x32_bf16 v[10:13], v[150:153], v[174:177], v[10:13]
	v_mfma_f32_16x16x32_bf16 v[6:9], v[158:161], v[174:177], v[6:9]
	v_mfma_f32_16x16x32_bf16 v[2:5], v[150:153], v[186:189], v[2:5]
	v_mfma_f32_16x16x32_bf16 v[126:129], v[158:161], v[186:189], v[126:129]
	v_mfma_f32_16x16x32_bf16 v[122:125], v[150:153], v[190:193], v[122:125]
	v_mfma_f32_16x16x32_bf16 v[118:121], v[158:161], v[190:193], v[118:121]
	s_setprio 0
	s_barrier
	ds_read_b128 v[130:133], v194
	ds_read_b128 v[134:137], v224
	ds_read_b128 v[138:141], v225
	ds_read_b128 v[142:145], v228
	ds_read_b128 v[146:149], v229
	ds_read_b128 v[150:153], v230
	ds_read_b128 v[154:157], v231
	ds_read_b128 v[158:161], v233
	s_addk_i32 s61, 0x2000
	s_mov_b32 m0, s26
	ds_read_b128 v[162:165], v221 offset:32768
	ds_read_b128 v[166:169], v221 offset:34816
	ds_read_b128 v[170:173], v222 offset:32768
	ds_read_b128 v[174:177], v222 offset:34816
	ds_read_b128 v[178:181], v221 offset:36864
	ds_read_b128 v[182:185], v221 offset:38912
	ds_read_b128 v[186:189], v222 offset:36864
	ds_read_b128 v[190:193], v222 offset:38912
	buffer_load_dwordx4 v207, s[4:7], s61 offen lds
	s_mov_b32 m0, s27
	s_nop 0
	buffer_load_dwordx4 v209, s[4:7], s61 offen lds
	s_waitcnt vmcnt(8)
	s_waitcnt lgkmcnt(0)
	s_barrier
	s_setprio 1
	v_mfma_f32_16x16x32_bf16 v[114:117], v[130:133], v[162:165], v[114:117]
	v_mfma_f32_16x16x32_bf16 v[110:113], v[138:141], v[162:165], v[110:113]
	v_mfma_f32_16x16x32_bf16 v[106:109], v[130:133], v[166:169], v[106:109]
	v_mfma_f32_16x16x32_bf16 v[102:105], v[138:141], v[166:169], v[102:105]
	v_mfma_f32_16x16x32_bf16 v[98:101], v[130:133], v[178:181], v[98:101]
	v_mfma_f32_16x16x32_bf16 v[94:97], v[138:141], v[178:181], v[94:97]
	v_mfma_f32_16x16x32_bf16 v[90:93], v[130:133], v[182:185], v[90:93]
	v_mfma_f32_16x16x32_bf16 v[86:89], v[138:141], v[182:185], v[86:89]
	v_mfma_f32_16x16x32_bf16 v[114:117], v[134:137], v[170:173], v[114:117]
	v_mfma_f32_16x16x32_bf16 v[110:113], v[142:145], v[170:173], v[110:113]
	v_mfma_f32_16x16x32_bf16 v[106:109], v[134:137], v[174:177], v[106:109]
	v_mfma_f32_16x16x32_bf16 v[102:105], v[142:145], v[174:177], v[102:105]
	v_mfma_f32_16x16x32_bf16 v[98:101], v[134:137], v[186:189], v[98:101]
	v_mfma_f32_16x16x32_bf16 v[94:97], v[142:145], v[186:189], v[94:97]
	v_mfma_f32_16x16x32_bf16 v[90:93], v[134:137], v[190:193], v[90:93]
	v_mfma_f32_16x16x32_bf16 v[86:89], v[142:145], v[190:193], v[86:89]
	v_mfma_f32_16x16x32_bf16 v[82:85], v[146:149], v[162:165], v[82:85]
	v_mfma_f32_16x16x32_bf16 v[74:77], v[154:157], v[162:165], v[74:77]
	v_mfma_f32_16x16x32_bf16 v[70:73], v[146:149], v[166:169], v[70:73]
	v_mfma_f32_16x16x32_bf16 v[66:69], v[154:157], v[166:169], v[66:69]
	v_mfma_f32_16x16x32_bf16 v[62:65], v[146:149], v[178:181], v[62:65]
	v_mfma_f32_16x16x32_bf16 v[58:61], v[154:157], v[178:181], v[58:61]
	v_mfma_f32_16x16x32_bf16 v[54:57], v[146:149], v[182:185], v[54:57]
	v_mfma_f32_16x16x32_bf16 v[50:53], v[154:157], v[182:185], v[50:53]
	v_mfma_f32_16x16x32_bf16 v[82:85], v[150:153], v[170:173], v[82:85]
	v_mfma_f32_16x16x32_bf16 v[74:77], v[158:161], v[170:173], v[74:77]
	v_mfma_f32_16x16x32_bf16 v[70:73], v[150:153], v[174:177], v[70:73]
	v_mfma_f32_16x16x32_bf16 v[66:69], v[158:161], v[174:177], v[66:69]
	v_mfma_f32_16x16x32_bf16 v[62:65], v[150:153], v[186:189], v[62:65]
	v_mfma_f32_16x16x32_bf16 v[58:61], v[158:161], v[186:189], v[58:61]
	v_mfma_f32_16x16x32_bf16 v[54:57], v[150:153], v[190:193], v[54:57]
	v_mfma_f32_16x16x32_bf16 v[50:53], v[158:161], v[190:193], v[50:53]
	s_setprio 0
	s_barrier
	s_mov_b32 m0, s29
	s_add_i32 s61, s60, 0x80
	ds_read_b128 v[162:165], v221 offset:49152
	ds_read_b128 v[166:169], v221 offset:51200
	ds_read_b128 v[170:173], v222 offset:49152
	ds_read_b128 v[174:177], v222 offset:51200
	ds_read_b128 v[178:181], v221 offset:53248
	ds_read_b128 v[182:185], v221 offset:55296
	ds_read_b128 v[186:189], v222 offset:53248
	ds_read_b128 v[190:193], v222 offset:55296
	buffer_load_dwordx4 v208, s[4:7], s61 offen lds
	s_mov_b32 m0, s30
	s_add_i32 s60, s60, 0x40080
	buffer_load_dwordx4 v210, s[4:7], s61 offen lds
	s_mov_b32 m0, s35
	s_nop 0
	buffer_load_dwordx4 v208, s[4:7], s60 offen lds
	s_mov_b32 m0, s36
	s_nop 0
	buffer_load_dwordx4 v210, s[4:7], s60 offen lds
	s_mov_b32 m0, s31
	s_nop 0
	buffer_load_dwordx4 v207, s[4:7], s59 offen lds
	s_mov_b32 m0, s34
	s_nop 0
	buffer_load_dwordx4 v209, s[4:7], s59 offen lds
	s_waitcnt vmcnt(8)
	s_waitcnt lgkmcnt(0)
	s_barrier
	s_setprio 1
	v_mfma_f32_16x16x32_bf16 v[78:81], v[130:133], v[162:165], v[78:81]
	v_mfma_f32_16x16x32_bf16 v[46:49], v[138:141], v[162:165], v[46:49]
	v_mfma_f32_16x16x32_bf16 v[42:45], v[130:133], v[166:169], v[42:45]
	v_mfma_f32_16x16x32_bf16 v[38:41], v[138:141], v[166:169], v[38:41]
	v_mfma_f32_16x16x32_bf16 v[34:37], v[130:133], v[178:181], v[34:37]
	v_mfma_f32_16x16x32_bf16 v[30:33], v[138:141], v[178:181], v[30:33]
	v_mfma_f32_16x16x32_bf16 v[26:29], v[130:133], v[182:185], v[26:29]
	v_mfma_f32_16x16x32_bf16 v[22:25], v[138:141], v[182:185], v[22:25]
	v_mfma_f32_16x16x32_bf16 v[78:81], v[134:137], v[170:173], v[78:81]
	v_mfma_f32_16x16x32_bf16 v[46:49], v[142:145], v[170:173], v[46:49]
	v_mfma_f32_16x16x32_bf16 v[42:45], v[134:137], v[174:177], v[42:45]
	v_mfma_f32_16x16x32_bf16 v[38:41], v[142:145], v[174:177], v[38:41]
	v_mfma_f32_16x16x32_bf16 v[34:37], v[134:137], v[186:189], v[34:37]
	v_mfma_f32_16x16x32_bf16 v[30:33], v[142:145], v[186:189], v[30:33]
	v_mfma_f32_16x16x32_bf16 v[26:29], v[134:137], v[190:193], v[26:29]
	v_mfma_f32_16x16x32_bf16 v[22:25], v[142:145], v[190:193], v[22:25]
	v_mfma_f32_16x16x32_bf16 v[18:21], v[146:149], v[162:165], v[18:21]
	v_mfma_f32_16x16x32_bf16 v[14:17], v[154:157], v[162:165], v[14:17]
	v_mfma_f32_16x16x32_bf16 v[10:13], v[146:149], v[166:169], v[10:13]
	v_mfma_f32_16x16x32_bf16 v[6:9], v[154:157], v[166:169], v[6:9]
	v_mfma_f32_16x16x32_bf16 v[2:5], v[146:149], v[178:181], v[2:5]
	v_mfma_f32_16x16x32_bf16 v[126:129], v[154:157], v[178:181], v[126:129]
	v_mfma_f32_16x16x32_bf16 v[122:125], v[146:149], v[182:185], v[122:125]
	v_mfma_f32_16x16x32_bf16 v[118:121], v[154:157], v[182:185], v[118:121]
	v_mfma_f32_16x16x32_bf16 v[18:21], v[150:153], v[170:173], v[18:21]
	v_mfma_f32_16x16x32_bf16 v[14:17], v[158:161], v[170:173], v[14:17]
	v_mfma_f32_16x16x32_bf16 v[10:13], v[150:153], v[174:177], v[10:13]
	v_mfma_f32_16x16x32_bf16 v[6:9], v[158:161], v[174:177], v[6:9]
	v_mfma_f32_16x16x32_bf16 v[2:5], v[150:153], v[186:189], v[2:5]
	v_mfma_f32_16x16x32_bf16 v[126:129], v[158:161], v[186:189], v[126:129]
	v_mfma_f32_16x16x32_bf16 v[122:125], v[150:153], v[190:193], v[122:125]
	v_mfma_f32_16x16x32_bf16 v[118:121], v[158:161], v[190:193], v[118:121]
	s_setprio 0
	s_barrier
	s_add_i32 s58, s58, 2
	s_addk_i32 s33, 0x100
	s_addk_i32 s57, 0x100
	s_cmp_gt_u32 s58, 13
	s_cbranch_scc0 .LBB0_233
	s_and_b64 vcc, exec, s[16:17]
	s_cbranch_vccz .LBB0_236
	s_barrier

.LBB0_546:
	ds_read_b128 v[130:133], v211
	ds_read_b128 v[134:137], v212
	ds_read_b128 v[138:141], v213
	ds_read_b128 v[142:145], v214
	ds_read_b128 v[146:149], v215
	ds_read_b128 v[150:153], v216
	ds_read_b128 v[154:157], v217
	ds_read_b128 v[158:161], v218
	s_add_i32 s4, s62, 0x80
	s_cmp_eq_u32 s63, s78
	s_cselect_b32 s84, s64, s4
	s_cselect_b32 s82, s33, s59
	s_cselect_b32 s81, s65, s61
	s_cselect_b32 s80, s56, s60
	s_add_i32 s79, s84, 0x80
	s_add_i32 s83, s60, s62
	s_mov_b32 s4, s70
	s_mov_b32 m0, s43
	ds_read_b128 v[162:165], v219
	ds_read_b128 v[166:169], v219 offset:2048
	ds_read_b128 v[170:173], v220
	ds_read_b128 v[174:177], v220 offset:2048
	ds_read_b128 v[178:181], v219 offset:4096
	ds_read_b128 v[182:185], v219 offset:6144
	ds_read_b128 v[186:189], v220 offset:4096
	ds_read_b128 v[190:193], v220 offset:6144
	buffer_load_dwordx4 v194, s[4:7], s83 offen lds
	s_mov_b32 m0, s44
	s_nop 0
	buffer_load_dwordx4 v222, s[4:7], s83 offen lds
	s_waitcnt vmcnt(8)
	s_waitcnt lgkmcnt(0)
	s_barrier
	s_setprio 1
	v_mfma_f32_16x16x32_bf16 v[126:129], v[130:133], v[162:165], v[126:129]
	v_mfma_f32_16x16x32_bf16 v[122:125], v[138:141], v[162:165], v[122:125]
	v_mfma_f32_16x16x32_bf16 v[118:121], v[130:133], v[166:169], v[118:121]
	v_mfma_f32_16x16x32_bf16 v[114:117], v[138:141], v[166:169], v[114:117]
	v_mfma_f32_16x16x32_bf16 v[110:113], v[130:133], v[178:181], v[110:113]
	v_mfma_f32_16x16x32_bf16 v[106:109], v[138:141], v[178:181], v[106:109]
	v_mfma_f32_16x16x32_bf16 v[102:105], v[130:133], v[182:185], v[102:105]
	v_mfma_f32_16x16x32_bf16 v[98:101], v[138:141], v[182:185], v[98:101]
	v_mfma_f32_16x16x32_bf16 v[126:129], v[134:137], v[170:173], v[126:129]
	v_mfma_f32_16x16x32_bf16 v[122:125], v[142:145], v[170:173], v[122:125]
	v_mfma_f32_16x16x32_bf16 v[118:121], v[134:137], v[174:177], v[118:121]
	v_mfma_f32_16x16x32_bf16 v[114:117], v[142:145], v[174:177], v[114:117]
	v_mfma_f32_16x16x32_bf16 v[110:113], v[134:137], v[186:189], v[110:113]
	v_mfma_f32_16x16x32_bf16 v[106:109], v[142:145], v[186:189], v[106:109]
	v_mfma_f32_16x16x32_bf16 v[102:105], v[134:137], v[190:193], v[102:105]
	v_mfma_f32_16x16x32_bf16 v[98:101], v[142:145], v[190:193], v[98:101]
	v_mfma_f32_16x16x32_bf16 v[94:97], v[146:149], v[162:165], v[94:97]
	v_mfma_f32_16x16x32_bf16 v[90:93], v[154:157], v[162:165], v[90:93]
	v_mfma_f32_16x16x32_bf16 v[86:89], v[146:149], v[166:169], v[86:89]
	v_mfma_f32_16x16x32_bf16 v[82:85], v[154:157], v[166:169], v[82:85]
	v_mfma_f32_16x16x32_bf16 v[78:81], v[146:149], v[178:181], v[78:81]
	v_mfma_f32_16x16x32_bf16 v[74:77], v[154:157], v[178:181], v[74:77]
	v_mfma_f32_16x16x32_bf16 v[70:73], v[146:149], v[182:185], v[70:73]
	v_mfma_f32_16x16x32_bf16 v[66:69], v[154:157], v[182:185], v[66:69]
	v_mfma_f32_16x16x32_bf16 v[94:97], v[150:153], v[170:173], v[94:97]
	v_mfma_f32_16x16x32_bf16 v[90:93], v[158:161], v[170:173], v[90:93]
	v_mfma_f32_16x16x32_bf16 v[86:89], v[150:153], v[174:177], v[86:89]
	v_mfma_f32_16x16x32_bf16 v[82:85], v[158:161], v[174:177], v[82:85]
	v_mfma_f32_16x16x32_bf16 v[78:81], v[150:153], v[186:189], v[78:81]
	v_mfma_f32_16x16x32_bf16 v[74:77], v[158:161], v[186:189], v[74:77]
	v_mfma_f32_16x16x32_bf16 v[70:73], v[150:153], v[190:193], v[70:73]
	v_mfma_f32_16x16x32_bf16 v[66:69], v[158:161], v[190:193], v[66:69]
	s_setprio 0
	s_barrier
	s_cmp_eq_u32 s82, 0
	s_cselect_b64 s[82:83], -1, 0
	v_cndmask_b32_e64 v233, v200, 0, s[82:83]
	s_mov_b32 m0, s25
	v_sub_u32_e32 v233, v201, v233
	v_cndmask_b32_e64 v234, v203, 0, s[82:83]
	ds_read_b128 v[162:165], v219 offset:16384
	ds_read_b128 v[166:169], v219 offset:18432
	ds_read_b128 v[170:173], v220 offset:16384
	ds_read_b128 v[174:177], v220 offset:18432
	ds_read_b128 v[178:181], v219 offset:20480
	ds_read_b128 v[182:185], v219 offset:22528
	ds_read_b128 v[186:189], v220 offset:20480
	ds_read_b128 v[190:193], v220 offset:22528
	buffer_load_dwordx4 v233, s[4:7], s81 offen lds
	v_sub_u32_e32 v234, v204, v234
	s_mov_b32 m0, s26
	s_add_i32 s85, s81, s80
	buffer_load_dwordx4 v234, s[4:7], s81 offen lds
	s_mov_b32 m0, s27
	v_cndmask_b32_e64 v235, v205, 0, s[82:83]
	buffer_load_dwordx4 v233, s[4:7], s85 offen lds
	s_mov_b32 m0, s28
	v_sub_u32_e32 v235, v1, v235
	buffer_load_dwordx4 v234, s[4:7], s85 offen lds
	s_mov_b32 m0, s24
	v_cndmask_b32_e64 v236, v206, 0, s[82:83]
	buffer_load_dwordx4 v235, s[4:7], s84 offen lds
	v_sub_u32_e32 v236, v202, v236
	s_mov_b32 m0, s29
	s_nop 0
	buffer_load_dwordx4 v236, s[4:7], s84 offen lds
	s_waitcnt vmcnt(8)
	s_waitcnt lgkmcnt(0)
	s_barrier
	s_setprio 1
	v_mfma_f32_16x16x32_bf16 v[62:65], v[130:133], v[162:165], v[62:65]
	v_mfma_f32_16x16x32_bf16 v[58:61], v[138:141], v[162:165], v[58:61]
	v_mfma_f32_16x16x32_bf16 v[54:57], v[130:133], v[166:169], v[54:57]
	v_mfma_f32_16x16x32_bf16 v[50:53], v[138:141], v[166:169], v[50:53]
	v_mfma_f32_16x16x32_bf16 v[46:49], v[130:133], v[178:181], v[46:49]
	v_mfma_f32_16x16x32_bf16 v[42:45], v[138:141], v[178:181], v[42:45]
	v_mfma_f32_16x16x32_bf16 v[38:41], v[130:133], v[182:185], v[38:41]
	v_mfma_f32_16x16x32_bf16 v[34:37], v[138:141], v[182:185], v[34:37]
	v_mfma_f32_16x16x32_bf16 v[62:65], v[134:137], v[170:173], v[62:65]
	v_mfma_f32_16x16x32_bf16 v[58:61], v[142:145], v[170:173], v[58:61]
	v_mfma_f32_16x16x32_bf16 v[54:57], v[134:137], v[174:177], v[54:57]
	v_mfma_f32_16x16x32_bf16 v[50:53], v[142:145], v[174:177], v[50:53]
	v_mfma_f32_16x16x32_bf16 v[46:49], v[134:137], v[186:189], v[46:49]
	v_mfma_f32_16x16x32_bf16 v[42:45], v[142:145], v[186:189], v[42:45]
	v_mfma_f32_16x16x32_bf16 v[38:41], v[134:137], v[190:193], v[38:41]
	v_mfma_f32_16x16x32_bf16 v[34:37], v[142:145], v[190:193], v[34:37]
	v_mfma_f32_16x16x32_bf16 v[30:33], v[146:149], v[162:165], v[30:33]
	v_mfma_f32_16x16x32_bf16 v[26:29], v[154:157], v[162:165], v[26:29]
	v_mfma_f32_16x16x32_bf16 v[22:25], v[146:149], v[166:169], v[22:25]
	v_mfma_f32_16x16x32_bf16 v[18:21], v[154:157], v[166:169], v[18:21]
	v_mfma_f32_16x16x32_bf16 v[14:17], v[146:149], v[178:181], v[14:17]
	v_mfma_f32_16x16x32_bf16 v[10:13], v[154:157], v[178:181], v[10:13]
	v_mfma_f32_16x16x32_bf16 v[6:9], v[146:149], v[182:185], v[6:9]
	v_mfma_f32_16x16x32_bf16 v[2:5], v[154:157], v[182:185], v[2:5]
	v_mfma_f32_16x16x32_bf16 v[30:33], v[150:153], v[170:173], v[30:33]
	v_mfma_f32_16x16x32_bf16 v[26:29], v[158:161], v[170:173], v[26:29]
	v_mfma_f32_16x16x32_bf16 v[22:25], v[150:153], v[174:177], v[22:25]
	v_mfma_f32_16x16x32_bf16 v[18:21], v[158:161], v[174:177], v[18:21]
	v_mfma_f32_16x16x32_bf16 v[14:17], v[150:153], v[186:189], v[14:17]
	v_mfma_f32_16x16x32_bf16 v[10:13], v[158:161], v[186:189], v[10:13]
	v_mfma_f32_16x16x32_bf16 v[6:9], v[150:153], v[190:193], v[6:9]
	v_mfma_f32_16x16x32_bf16 v[2:5], v[158:161], v[190:193], v[2:5]
	s_setprio 0
	s_barrier
	ds_read_b128 v[130:133], v223
	ds_read_b128 v[134:137], v224
	ds_read_b128 v[138:141], v225
	ds_read_b128 v[142:145], v227
	ds_read_b128 v[146:149], v228
	ds_read_b128 v[150:153], v229
	ds_read_b128 v[154:157], v230
	ds_read_b128 v[158:161], v231
	s_add_i32 s84, s84, s80
	s_mov_b32 m0, s30
	ds_read_b128 v[162:165], v219 offset:32768
	ds_read_b128 v[166:169], v219 offset:34816
	ds_read_b128 v[170:173], v220 offset:32768
	ds_read_b128 v[174:177], v220 offset:34816
	ds_read_b128 v[178:181], v219 offset:36864
	ds_read_b128 v[182:185], v219 offset:38912
	ds_read_b128 v[186:189], v220 offset:36864
	ds_read_b128 v[190:193], v220 offset:38912
	buffer_load_dwordx4 v235, s[4:7], s84 offen lds
	s_mov_b32 m0, s31
	s_nop 0
	buffer_load_dwordx4 v236, s[4:7], s84 offen lds
	s_waitcnt vmcnt(8)
	s_waitcnt lgkmcnt(0)
	s_barrier
	s_setprio 1
	v_mfma_f32_16x16x32_bf16 v[126:129], v[130:133], v[162:165], v[126:129]
	v_mfma_f32_16x16x32_bf16 v[122:125], v[138:141], v[162:165], v[122:125]
	v_mfma_f32_16x16x32_bf16 v[118:121], v[130:133], v[166:169], v[118:121]
	v_mfma_f32_16x16x32_bf16 v[114:117], v[138:141], v[166:169], v[114:117]
	v_mfma_f32_16x16x32_bf16 v[110:113], v[130:133], v[178:181], v[110:113]
	v_mfma_f32_16x16x32_bf16 v[106:109], v[138:141], v[178:181], v[106:109]
	v_mfma_f32_16x16x32_bf16 v[102:105], v[130:133], v[182:185], v[102:105]
	v_mfma_f32_16x16x32_bf16 v[98:101], v[138:141], v[182:185], v[98:101]
	v_mfma_f32_16x16x32_bf16 v[126:129], v[134:137], v[170:173], v[126:129]
	v_mfma_f32_16x16x32_bf16 v[122:125], v[142:145], v[170:173], v[122:125]
	v_mfma_f32_16x16x32_bf16 v[118:121], v[134:137], v[174:177], v[118:121]
	v_mfma_f32_16x16x32_bf16 v[114:117], v[142:145], v[174:177], v[114:117]
	v_mfma_f32_16x16x32_bf16 v[110:113], v[134:137], v[186:189], v[110:113]
	v_mfma_f32_16x16x32_bf16 v[106:109], v[142:145], v[186:189], v[106:109]
	v_mfma_f32_16x16x32_bf16 v[102:105], v[134:137], v[190:193], v[102:105]
	v_mfma_f32_16x16x32_bf16 v[98:101], v[142:145], v[190:193], v[98:101]
	v_mfma_f32_16x16x32_bf16 v[94:97], v[146:149], v[162:165], v[94:97]
	v_mfma_f32_16x16x32_bf16 v[90:93], v[154:157], v[162:165], v[90:93]
	v_mfma_f32_16x16x32_bf16 v[86:89], v[146:149], v[166:169], v[86:89]
	v_mfma_f32_16x16x32_bf16 v[82:85], v[154:157], v[166:169], v[82:85]
	v_mfma_f32_16x16x32_bf16 v[78:81], v[146:149], v[178:181], v[78:81]
	v_mfma_f32_16x16x32_bf16 v[74:77], v[154:157], v[178:181], v[74:77]
	v_mfma_f32_16x16x32_bf16 v[70:73], v[146:149], v[182:185], v[70:73]
	v_mfma_f32_16x16x32_bf16 v[66:69], v[154:157], v[182:185], v[66:69]
	v_mfma_f32_16x16x32_bf16 v[94:97], v[150:153], v[170:173], v[94:97]
	v_mfma_f32_16x16x32_bf16 v[90:93], v[158:161], v[170:173], v[90:93]
	v_mfma_f32_16x16x32_bf16 v[86:89], v[150:153], v[174:177], v[86:89]
	v_mfma_f32_16x16x32_bf16 v[82:85], v[158:161], v[174:177], v[82:85]
	v_mfma_f32_16x16x32_bf16 v[78:81], v[150:153], v[186:189], v[78:81]
	v_mfma_f32_16x16x32_bf16 v[74:77], v[158:161], v[186:189], v[74:77]
	v_mfma_f32_16x16x32_bf16 v[70:73], v[150:153], v[190:193], v[70:73]
	v_mfma_f32_16x16x32_bf16 v[66:69], v[158:161], v[190:193], v[66:69]
	s_setprio 0
	s_barrier
	s_mov_b32 m0, s36
	s_addk_i32 s81, 0x80
	ds_read_b128 v[162:165], v219 offset:49152
	ds_read_b128 v[166:169], v219 offset:51200
	ds_read_b128 v[170:173], v220 offset:49152
	ds_read_b128 v[174:177], v220 offset:51200
	ds_read_b128 v[178:181], v219 offset:53248
	ds_read_b128 v[182:185], v219 offset:55296
	ds_read_b128 v[186:189], v220 offset:53248
	ds_read_b128 v[190:193], v220 offset:55296
	buffer_load_dwordx4 v233, s[4:7], s81 offen lds
	s_mov_b32 m0, s37
	s_nop 0
	buffer_load_dwordx4 v234, s[4:7], s81 offen lds
	s_add_i32 s81, s81, s80
	s_mov_b32 m0, s40
	s_nop 0
	buffer_load_dwordx4 v233, s[4:7], s81 offen lds
	s_mov_b32 m0, s41
	s_nop 0
	buffer_load_dwordx4 v234, s[4:7], s81 offen lds
	s_mov_b32 m0, s38
	s_nop 0
	buffer_load_dwordx4 v235, s[4:7], s79 offen lds
	s_mov_b32 m0, s39
	s_nop 0
	buffer_load_dwordx4 v236, s[4:7], s79 offen lds
	s_waitcnt vmcnt(8)
	s_waitcnt lgkmcnt(0)
	s_barrier
	s_setprio 1
	v_mfma_f32_16x16x32_bf16 v[62:65], v[130:133], v[162:165], v[62:65]
	v_mfma_f32_16x16x32_bf16 v[58:61], v[138:141], v[162:165], v[58:61]
	v_mfma_f32_16x16x32_bf16 v[54:57], v[130:133], v[166:169], v[54:57]
	v_mfma_f32_16x16x32_bf16 v[50:53], v[138:141], v[166:169], v[50:53]
	v_mfma_f32_16x16x32_bf16 v[46:49], v[130:133], v[178:181], v[46:49]
	v_mfma_f32_16x16x32_bf16 v[42:45], v[138:141], v[178:181], v[42:45]
	v_mfma_f32_16x16x32_bf16 v[38:41], v[130:133], v[182:185], v[38:41]
	v_mfma_f32_16x16x32_bf16 v[34:37], v[138:141], v[182:185], v[34:37]
	v_mfma_f32_16x16x32_bf16 v[62:65], v[134:137], v[170:173], v[62:65]
	v_mfma_f32_16x16x32_bf16 v[58:61], v[142:145], v[170:173], v[58:61]
	v_mfma_f32_16x16x32_bf16 v[54:57], v[134:137], v[174:177], v[54:57]
	v_mfma_f32_16x16x32_bf16 v[50:53], v[142:145], v[174:177], v[50:53]
	v_mfma_f32_16x16x32_bf16 v[46:49], v[134:137], v[186:189], v[46:49]
	v_mfma_f32_16x16x32_bf16 v[42:45], v[142:145], v[186:189], v[42:45]
	v_mfma_f32_16x16x32_bf16 v[38:41], v[134:137], v[190:193], v[38:41]
	v_mfma_f32_16x16x32_bf16 v[34:37], v[142:145], v[190:193], v[34:37]
	v_mfma_f32_16x16x32_bf16 v[30:33], v[146:149], v[162:165], v[30:33]
	v_mfma_f32_16x16x32_bf16 v[26:29], v[154:157], v[162:165], v[26:29]
	v_mfma_f32_16x16x32_bf16 v[22:25], v[146:149], v[166:169], v[22:25]
	v_mfma_f32_16x16x32_bf16 v[18:21], v[154:157], v[166:169], v[18:21]
	v_mfma_f32_16x16x32_bf16 v[14:17], v[146:149], v[178:181], v[14:17]
	v_mfma_f32_16x16x32_bf16 v[10:13], v[154:157], v[178:181], v[10:13]
	v_mfma_f32_16x16x32_bf16 v[6:9], v[146:149], v[182:185], v[6:9]
	v_mfma_f32_16x16x32_bf16 v[2:5], v[154:157], v[182:185], v[2:5]
	v_mfma_f32_16x16x32_bf16 v[30:33], v[150:153], v[170:173], v[30:33]
	v_mfma_f32_16x16x32_bf16 v[26:29], v[158:161], v[170:173], v[26:29]
	v_mfma_f32_16x16x32_bf16 v[22:25], v[150:153], v[174:177], v[22:25]
	v_mfma_f32_16x16x32_bf16 v[18:21], v[158:161], v[174:177], v[18:21]
	v_mfma_f32_16x16x32_bf16 v[14:17], v[150:153], v[186:189], v[14:17]
	v_mfma_f32_16x16x32_bf16 v[10:13], v[158:161], v[186:189], v[10:13]
	v_mfma_f32_16x16x32_bf16 v[6:9], v[150:153], v[190:193], v[6:9]
	v_mfma_f32_16x16x32_bf16 v[2:5], v[158:161], v[190:193], v[2:5]
	s_setprio 0
	s_barrier
	s_add_i32 s4, s78, 2
	s_addk_i32 s62, 0x100
	s_addk_i32 s61, 0x100
	s_cmp_ge_u32 s78, s63
	s_mov_b32 s78, s4
	s_cbranch_scc0 .LBB0_546
	s_and_b64 vcc, exec, s[12:13]
	s_cbranch_vccz .LBB0_549
	s_barrier

.LBB0_841:
	ds_read_b128 v[130:133], v240
	ds_read_b128 v[134:137], v241
	ds_read_b128 v[138:141], v242
	ds_read_b128 v[142:145], v243
	ds_read_b128 v[146:149], v244
	ds_read_b128 v[150:153], v245
	ds_read_b128 v[154:157], v246
	ds_read_b128 v[158:161], v247
	s_add_i32 s8, s42, s5
	s_add_i32 s19, s34, s5
	s_add_i32 s18, s8, 0x800
	s_addk_i32 s19, 0x800
	s_cmp_eq_u32 s5, 0
	s_cselect_b32 s20, s0, s18
	s_cselect_b32 s19, s1, s19
	s_add_i32 s18, s20, 0x80
	s_add_i32 s21, s8, 0x40780
	s_mov_b32 s8, s70
	s_mov_b32 m0, s52
	ds_read_b128 v[162:165], v248
	ds_read_b128 v[166:169], v248 offset:2048
	ds_read_b128 v[170:173], v249
	ds_read_b128 v[174:177], v249 offset:2048
	ds_read_b128 v[178:181], v248 offset:4096
	ds_read_b128 v[182:185], v248 offset:6144
	ds_read_b128 v[186:189], v249 offset:4096
	ds_read_b128 v[190:193], v249 offset:6144
	buffer_load_dwordx4 v1, s[8:11], s21 offen lds
	s_mov_b32 m0, s53
	s_nop 0
	buffer_load_dwordx4 v234, s[8:11], s21 offen lds
	s_waitcnt vmcnt(8)
	s_waitcnt lgkmcnt(0)
	s_barrier
	s_setprio 1
	v_mfma_f32_16x16x32_bf16 v[74:77], v[130:133], v[162:165], v[74:77]
	v_mfma_f32_16x16x32_bf16 v[70:73], v[138:141], v[162:165], v[70:73]
	v_mfma_f32_16x16x32_bf16 v[66:69], v[130:133], v[166:169], v[66:69]
	v_mfma_f32_16x16x32_bf16 v[82:85], v[138:141], v[166:169], v[82:85]
	v_mfma_f32_16x16x32_bf16 v[78:81], v[130:133], v[178:181], v[78:81]
	v_mfma_f32_16x16x32_bf16 v[90:93], v[138:141], v[178:181], v[90:93]
	v_mfma_f32_16x16x32_bf16 v[86:89], v[130:133], v[182:185], v[86:89]
	v_mfma_f32_16x16x32_bf16 v[102:105], v[138:141], v[182:185], v[102:105]
	v_mfma_f32_16x16x32_bf16 v[74:77], v[134:137], v[170:173], v[74:77]
	v_mfma_f32_16x16x32_bf16 v[70:73], v[142:145], v[170:173], v[70:73]
	v_mfma_f32_16x16x32_bf16 v[66:69], v[134:137], v[174:177], v[66:69]
	v_mfma_f32_16x16x32_bf16 v[82:85], v[142:145], v[174:177], v[82:85]
	v_mfma_f32_16x16x32_bf16 v[78:81], v[134:137], v[186:189], v[78:81]
	v_mfma_f32_16x16x32_bf16 v[90:93], v[142:145], v[186:189], v[90:93]
	v_mfma_f32_16x16x32_bf16 v[86:89], v[134:137], v[190:193], v[86:89]
	v_mfma_f32_16x16x32_bf16 v[102:105], v[142:145], v[190:193], v[102:105]
	v_mfma_f32_16x16x32_bf16 v[98:101], v[146:149], v[162:165], v[98:101]
	v_mfma_f32_16x16x32_bf16 v[94:97], v[154:157], v[162:165], v[94:97]
	v_mfma_f32_16x16x32_bf16 v[106:109], v[146:149], v[166:169], v[106:109]
	v_mfma_f32_16x16x32_bf16 v[110:113], v[154:157], v[166:169], v[110:113]
	v_mfma_f32_16x16x32_bf16 v[114:117], v[146:149], v[178:181], v[114:117]
	v_mfma_f32_16x16x32_bf16 v[118:121], v[154:157], v[178:181], v[118:121]
	v_mfma_f32_16x16x32_bf16 v[122:125], v[146:149], v[182:185], v[122:125]
	v_mfma_f32_16x16x32_bf16 v[126:129], v[154:157], v[182:185], v[126:129]
	v_mfma_f32_16x16x32_bf16 v[98:101], v[150:153], v[170:173], v[98:101]
	v_mfma_f32_16x16x32_bf16 v[94:97], v[158:161], v[170:173], v[94:97]
	v_mfma_f32_16x16x32_bf16 v[106:109], v[150:153], v[174:177], v[106:109]
	v_mfma_f32_16x16x32_bf16 v[110:113], v[158:161], v[174:177], v[110:113]
	v_mfma_f32_16x16x32_bf16 v[114:117], v[150:153], v[186:189], v[114:117]
	v_mfma_f32_16x16x32_bf16 v[118:121], v[158:161], v[186:189], v[118:121]
	v_mfma_f32_16x16x32_bf16 v[122:125], v[150:153], v[190:193], v[122:125]
	v_mfma_f32_16x16x32_bf16 v[126:129], v[158:161], v[190:193], v[126:129]
	s_setprio 0
	s_barrier
	s_mov_b32 m0, s29
	ds_read_b128 v[162:165], v248 offset:16384
	ds_read_b128 v[166:169], v248 offset:18432
	ds_read_b128 v[170:173], v249 offset:16384
	ds_read_b128 v[174:177], v249 offset:18432
	ds_read_b128 v[178:181], v248 offset:20480
	ds_read_b128 v[182:185], v248 offset:22528
	ds_read_b128 v[186:189], v249 offset:20480
	ds_read_b128 v[190:193], v249 offset:22528
	buffer_load_dwordx4 v233, s[8:11], s19 offen lds
	s_mov_b32 m0, s30
	s_add_i32 s21, s19, 0x40000
	buffer_load_dwordx4 v235, s[8:11], s19 offen lds
	s_mov_b32 m0, s31
	s_nop 0
	buffer_load_dwordx4 v233, s[8:11], s21 offen lds
	s_mov_b32 m0, s35
	s_nop 0
	buffer_load_dwordx4 v235, s[8:11], s21 offen lds
	s_mov_b32 m0, s28
	s_nop 0
	buffer_load_dwordx4 v1, s[8:11], s20 offen lds
	s_mov_b32 m0, s38
	s_nop 0
	buffer_load_dwordx4 v234, s[8:11], s20 offen lds
	s_waitcnt vmcnt(8)
	s_waitcnt lgkmcnt(0)
	s_barrier
	s_setprio 1
	v_mfma_f32_16x16x32_bf16 v[10:13], v[130:133], v[162:165], v[10:13]
	v_mfma_f32_16x16x32_bf16 v[6:9], v[138:141], v[162:165], v[6:9]
	v_mfma_f32_16x16x32_bf16 v[2:5], v[130:133], v[166:169], v[2:5]
	v_mfma_f32_16x16x32_bf16 v[18:21], v[138:141], v[166:169], v[18:21]
	v_mfma_f32_16x16x32_bf16 v[14:17], v[130:133], v[178:181], v[14:17]
	v_mfma_f32_16x16x32_bf16 v[26:29], v[138:141], v[178:181], v[26:29]
	v_mfma_f32_16x16x32_bf16 v[22:25], v[130:133], v[182:185], v[22:25]
	v_mfma_f32_16x16x32_bf16 v[38:41], v[138:141], v[182:185], v[38:41]
	v_mfma_f32_16x16x32_bf16 v[10:13], v[134:137], v[170:173], v[10:13]
	v_mfma_f32_16x16x32_bf16 v[6:9], v[142:145], v[170:173], v[6:9]
	v_mfma_f32_16x16x32_bf16 v[2:5], v[134:137], v[174:177], v[2:5]
	v_mfma_f32_16x16x32_bf16 v[18:21], v[142:145], v[174:177], v[18:21]
	v_mfma_f32_16x16x32_bf16 v[14:17], v[134:137], v[186:189], v[14:17]
	v_mfma_f32_16x16x32_bf16 v[26:29], v[142:145], v[186:189], v[26:29]
	v_mfma_f32_16x16x32_bf16 v[22:25], v[134:137], v[190:193], v[22:25]
	v_mfma_f32_16x16x32_bf16 v[38:41], v[142:145], v[190:193], v[38:41]
	v_mfma_f32_16x16x32_bf16 v[34:37], v[146:149], v[162:165], v[34:37]
	v_mfma_f32_16x16x32_bf16 v[30:33], v[154:157], v[162:165], v[30:33]
	v_mfma_f32_16x16x32_bf16 v[42:45], v[146:149], v[166:169], v[42:45]
	v_mfma_f32_16x16x32_bf16 v[46:49], v[154:157], v[166:169], v[46:49]
	v_mfma_f32_16x16x32_bf16 v[50:53], v[146:149], v[178:181], v[50:53]
	v_mfma_f32_16x16x32_bf16 v[54:57], v[154:157], v[178:181], v[54:57]
	v_mfma_f32_16x16x32_bf16 v[58:61], v[146:149], v[182:185], v[58:61]
	v_mfma_f32_16x16x32_bf16 v[62:65], v[154:157], v[182:185], v[62:65]
	v_mfma_f32_16x16x32_bf16 v[34:37], v[150:153], v[170:173], v[34:37]
	v_mfma_f32_16x16x32_bf16 v[30:33], v[158:161], v[170:173], v[30:33]
	v_mfma_f32_16x16x32_bf16 v[42:45], v[150:153], v[174:177], v[42:45]
	v_mfma_f32_16x16x32_bf16 v[46:49], v[158:161], v[174:177], v[46:49]
	v_mfma_f32_16x16x32_bf16 v[50:53], v[150:153], v[186:189], v[50:53]
	v_mfma_f32_16x16x32_bf16 v[54:57], v[158:161], v[186:189], v[54:57]
	v_mfma_f32_16x16x32_bf16 v[58:61], v[150:153], v[190:193], v[58:61]
	v_mfma_f32_16x16x32_bf16 v[62:65], v[158:161], v[190:193], v[62:65]
	s_setprio 0
	s_barrier
	ds_read_b128 v[130:133], v194
	ds_read_b128 v[134:137], v195
	ds_read_b128 v[138:141], v196
	ds_read_b128 v[142:145], v197
	ds_read_b128 v[146:149], v198
	ds_read_b128 v[150:153], v199
	ds_read_b128 v[154:157], v200
	ds_read_b128 v[158:161], v201
	s_add_i32 s20, s20, 0x40000
	s_mov_b32 m0, s39
	ds_read_b128 v[162:165], v248 offset:32768
	ds_read_b128 v[166:169], v248 offset:34816
	ds_read_b128 v[170:173], v249 offset:32768
	ds_read_b128 v[174:177], v249 offset:34816
	ds_read_b128 v[178:181], v248 offset:36864
	ds_read_b128 v[182:185], v248 offset:38912
	ds_read_b128 v[186:189], v249 offset:36864
	ds_read_b128 v[190:193], v249 offset:38912
	buffer_load_dwordx4 v1, s[8:11], s20 offen lds
	s_mov_b32 m0, s41
	s_nop 0
	buffer_load_dwordx4 v234, s[8:11], s20 offen lds
	s_waitcnt vmcnt(8)
	s_waitcnt lgkmcnt(0)
	s_barrier
	s_setprio 1
	v_mfma_f32_16x16x32_bf16 v[74:77], v[130:133], v[162:165], v[74:77]
	v_mfma_f32_16x16x32_bf16 v[70:73], v[138:141], v[162:165], v[70:73]
	v_mfma_f32_16x16x32_bf16 v[66:69], v[130:133], v[166:169], v[66:69]
	v_mfma_f32_16x16x32_bf16 v[82:85], v[138:141], v[166:169], v[82:85]
	v_mfma_f32_16x16x32_bf16 v[78:81], v[130:133], v[178:181], v[78:81]
	v_mfma_f32_16x16x32_bf16 v[90:93], v[138:141], v[178:181], v[90:93]
	v_mfma_f32_16x16x32_bf16 v[86:89], v[130:133], v[182:185], v[86:89]
	v_mfma_f32_16x16x32_bf16 v[102:105], v[138:141], v[182:185], v[102:105]
	v_mfma_f32_16x16x32_bf16 v[74:77], v[134:137], v[170:173], v[74:77]
	v_mfma_f32_16x16x32_bf16 v[70:73], v[142:145], v[170:173], v[70:73]
	v_mfma_f32_16x16x32_bf16 v[66:69], v[134:137], v[174:177], v[66:69]
	v_mfma_f32_16x16x32_bf16 v[82:85], v[142:145], v[174:177], v[82:85]
	v_mfma_f32_16x16x32_bf16 v[78:81], v[134:137], v[186:189], v[78:81]
	v_mfma_f32_16x16x32_bf16 v[90:93], v[142:145], v[186:189], v[90:93]
	v_mfma_f32_16x16x32_bf16 v[86:89], v[134:137], v[190:193], v[86:89]
	v_mfma_f32_16x16x32_bf16 v[102:105], v[142:145], v[190:193], v[102:105]
	v_mfma_f32_16x16x32_bf16 v[98:101], v[146:149], v[162:165], v[98:101]
	v_mfma_f32_16x16x32_bf16 v[94:97], v[154:157], v[162:165], v[94:97]
	v_mfma_f32_16x16x32_bf16 v[106:109], v[146:149], v[166:169], v[106:109]
	v_mfma_f32_16x16x32_bf16 v[110:113], v[154:157], v[166:169], v[110:113]
	v_mfma_f32_16x16x32_bf16 v[114:117], v[146:149], v[178:181], v[114:117]
	v_mfma_f32_16x16x32_bf16 v[118:121], v[154:157], v[178:181], v[118:121]
	v_mfma_f32_16x16x32_bf16 v[122:125], v[146:149], v[182:185], v[122:125]
	v_mfma_f32_16x16x32_bf16 v[126:129], v[154:157], v[182:185], v[126:129]
	v_mfma_f32_16x16x32_bf16 v[98:101], v[150:153], v[170:173], v[98:101]
	v_mfma_f32_16x16x32_bf16 v[94:97], v[158:161], v[170:173], v[94:97]
	v_mfma_f32_16x16x32_bf16 v[106:109], v[150:153], v[174:177], v[106:109]
	v_mfma_f32_16x16x32_bf16 v[110:113], v[158:161], v[174:177], v[110:113]
	v_mfma_f32_16x16x32_bf16 v[114:117], v[150:153], v[186:189], v[114:117]
	v_mfma_f32_16x16x32_bf16 v[118:121], v[158:161], v[186:189], v[118:121]
	v_mfma_f32_16x16x32_bf16 v[122:125], v[150:153], v[190:193], v[122:125]
	v_mfma_f32_16x16x32_bf16 v[126:129], v[158:161], v[190:193], v[126:129]
	s_setprio 0
	s_barrier
	s_mov_b32 m0, s44
	s_add_i32 s20, s19, 0x80
	ds_read_b128 v[162:165], v248 offset:49152
	ds_read_b128 v[166:169], v248 offset:51200
	ds_read_b128 v[170:173], v249 offset:49152
	ds_read_b128 v[174:177], v249 offset:51200
	ds_read_b128 v[178:181], v248 offset:53248
	ds_read_b128 v[182:185], v248 offset:55296
	ds_read_b128 v[186:189], v249 offset:53248
	ds_read_b128 v[190:193], v249 offset:55296
	buffer_load_dwordx4 v233, s[8:11], s20 offen lds
	s_mov_b32 m0, s45
	s_add_i32 s19, s19, 0x40080
	buffer_load_dwordx4 v235, s[8:11], s20 offen lds
	s_mov_b32 m0, s48
	s_nop 0
	buffer_load_dwordx4 v233, s[8:11], s19 offen lds
	s_mov_b32 m0, s49
	s_nop 0
	buffer_load_dwordx4 v235, s[8:11], s19 offen lds
	s_mov_b32 m0, s46
	s_nop 0
	buffer_load_dwordx4 v1, s[8:11], s18 offen lds
	s_mov_b32 m0, s47
	s_nop 0
	buffer_load_dwordx4 v234, s[8:11], s18 offen lds
	s_waitcnt vmcnt(8)
	s_waitcnt lgkmcnt(0)
	s_barrier
	s_setprio 1
	v_mfma_f32_16x16x32_bf16 v[10:13], v[130:133], v[162:165], v[10:13]
	v_mfma_f32_16x16x32_bf16 v[6:9], v[138:141], v[162:165], v[6:9]
	v_mfma_f32_16x16x32_bf16 v[2:5], v[130:133], v[166:169], v[2:5]
	v_mfma_f32_16x16x32_bf16 v[18:21], v[138:141], v[166:169], v[18:21]
	v_mfma_f32_16x16x32_bf16 v[14:17], v[130:133], v[178:181], v[14:17]
	v_mfma_f32_16x16x32_bf16 v[26:29], v[138:141], v[178:181], v[26:29]
	v_mfma_f32_16x16x32_bf16 v[22:25], v[130:133], v[182:185], v[22:25]
	v_mfma_f32_16x16x32_bf16 v[38:41], v[138:141], v[182:185], v[38:41]
	v_mfma_f32_16x16x32_bf16 v[10:13], v[134:137], v[170:173], v[10:13]
	v_mfma_f32_16x16x32_bf16 v[6:9], v[142:145], v[170:173], v[6:9]
	v_mfma_f32_16x16x32_bf16 v[2:5], v[134:137], v[174:177], v[2:5]
	v_mfma_f32_16x16x32_bf16 v[18:21], v[142:145], v[174:177], v[18:21]
	v_mfma_f32_16x16x32_bf16 v[14:17], v[134:137], v[186:189], v[14:17]
	v_mfma_f32_16x16x32_bf16 v[26:29], v[142:145], v[186:189], v[26:29]
	v_mfma_f32_16x16x32_bf16 v[22:25], v[134:137], v[190:193], v[22:25]
	v_mfma_f32_16x16x32_bf16 v[38:41], v[142:145], v[190:193], v[38:41]
	v_mfma_f32_16x16x32_bf16 v[34:37], v[146:149], v[162:165], v[34:37]
	v_mfma_f32_16x16x32_bf16 v[30:33], v[154:157], v[162:165], v[30:33]
	v_mfma_f32_16x16x32_bf16 v[42:45], v[146:149], v[166:169], v[42:45]
	v_mfma_f32_16x16x32_bf16 v[46:49], v[154:157], v[166:169], v[46:49]
	v_mfma_f32_16x16x32_bf16 v[50:53], v[146:149], v[178:181], v[50:53]
	v_mfma_f32_16x16x32_bf16 v[54:57], v[154:157], v[178:181], v[54:57]
	v_mfma_f32_16x16x32_bf16 v[58:61], v[146:149], v[182:185], v[58:61]
	v_mfma_f32_16x16x32_bf16 v[62:65], v[154:157], v[182:185], v[62:65]
	v_mfma_f32_16x16x32_bf16 v[34:37], v[150:153], v[170:173], v[34:37]
	v_mfma_f32_16x16x32_bf16 v[30:33], v[158:161], v[170:173], v[30:33]
	v_mfma_f32_16x16x32_bf16 v[42:45], v[150:153], v[174:177], v[42:45]
	v_mfma_f32_16x16x32_bf16 v[46:49], v[158:161], v[174:177], v[46:49]
	v_mfma_f32_16x16x32_bf16 v[50:53], v[150:153], v[186:189], v[50:53]
	v_mfma_f32_16x16x32_bf16 v[54:57], v[158:161], v[186:189], v[54:57]
	v_mfma_f32_16x16x32_bf16 v[58:61], v[150:153], v[190:193], v[58:61]
	v_mfma_f32_16x16x32_bf16 v[62:65], v[158:161], v[190:193], v[62:65]
	s_setprio 0
	s_barrier
	s_add_i32 s4, s4, 2
	s_addk_i32 s5, 0x100
	s_cmp_gt_u32 s4, 13
	s_cbranch_scc0 .LBB0_841
	s_and_b64 vcc, exec, s[16:17]
	s_cbranch_vccz .LBB0_844
	s_barrier

.LBB0_1122:
	ds_read_b128 v[130:133], v240
	ds_read_b128 v[134:137], v241
	ds_read_b128 v[138:141], v242
	ds_read_b128 v[142:145], v243
	ds_read_b128 v[146:149], v244
	ds_read_b128 v[150:153], v245
	ds_read_b128 v[154:157], v246
	ds_read_b128 v[158:161], v247
	s_add_i32 s8, s31, s53
	s_add_i32 s55, s26, s53
	s_add_i32 s54, s8, 0x800
	s_addk_i32 s55, 0x800
	s_cmp_eq_u32 s53, 0
	s_cselect_b32 s56, s4, s54
	s_cselect_b32 s55, s5, s55
	s_add_i32 s54, s56, 0x80
	s_add_i32 s57, s8, 0x40780
	s_mov_b32 s8, s70
	s_mov_b32 m0, s44
	ds_read_b128 v[162:165], v248
	ds_read_b128 v[166:169], v248 offset:2048
	ds_read_b128 v[170:173], v249
	ds_read_b128 v[174:177], v249 offset:2048
	ds_read_b128 v[178:181], v248 offset:4096
	ds_read_b128 v[182:185], v248 offset:6144
	ds_read_b128 v[186:189], v249 offset:4096
	ds_read_b128 v[190:193], v249 offset:6144
	buffer_load_dwordx4 v1, s[8:11], s57 offen lds
	s_mov_b32 m0, s45
	s_nop 0
	buffer_load_dwordx4 v234, s[8:11], s57 offen lds
	s_waitcnt vmcnt(8)
	s_waitcnt lgkmcnt(0)
	s_barrier
	s_setprio 1
	v_mfma_f32_16x16x32_bf16 v[126:129], v[130:133], v[162:165], v[126:129]
	v_mfma_f32_16x16x32_bf16 v[122:125], v[138:141], v[162:165], v[122:125]
	v_mfma_f32_16x16x32_bf16 v[118:121], v[130:133], v[166:169], v[118:121]
	v_mfma_f32_16x16x32_bf16 v[114:117], v[138:141], v[166:169], v[114:117]
	v_mfma_f32_16x16x32_bf16 v[110:113], v[130:133], v[178:181], v[110:113]
	v_mfma_f32_16x16x32_bf16 v[106:109], v[138:141], v[178:181], v[106:109]
	v_mfma_f32_16x16x32_bf16 v[102:105], v[130:133], v[182:185], v[102:105]
	v_mfma_f32_16x16x32_bf16 v[98:101], v[138:141], v[182:185], v[98:101]
	v_mfma_f32_16x16x32_bf16 v[126:129], v[134:137], v[170:173], v[126:129]
	v_mfma_f32_16x16x32_bf16 v[122:125], v[142:145], v[170:173], v[122:125]
	v_mfma_f32_16x16x32_bf16 v[118:121], v[134:137], v[174:177], v[118:121]
	v_mfma_f32_16x16x32_bf16 v[114:117], v[142:145], v[174:177], v[114:117]
	v_mfma_f32_16x16x32_bf16 v[110:113], v[134:137], v[186:189], v[110:113]
	v_mfma_f32_16x16x32_bf16 v[106:109], v[142:145], v[186:189], v[106:109]
	v_mfma_f32_16x16x32_bf16 v[102:105], v[134:137], v[190:193], v[102:105]
	v_mfma_f32_16x16x32_bf16 v[98:101], v[142:145], v[190:193], v[98:101]
	v_mfma_f32_16x16x32_bf16 v[94:97], v[146:149], v[162:165], v[94:97]
	v_mfma_f32_16x16x32_bf16 v[90:93], v[154:157], v[162:165], v[90:93]
	v_mfma_f32_16x16x32_bf16 v[86:89], v[146:149], v[166:169], v[86:89]
	v_mfma_f32_16x16x32_bf16 v[82:85], v[154:157], v[166:169], v[82:85]
	v_mfma_f32_16x16x32_bf16 v[78:81], v[146:149], v[178:181], v[78:81]
	v_mfma_f32_16x16x32_bf16 v[74:77], v[154:157], v[178:181], v[74:77]
	v_mfma_f32_16x16x32_bf16 v[70:73], v[146:149], v[182:185], v[70:73]
	v_mfma_f32_16x16x32_bf16 v[66:69], v[154:157], v[182:185], v[66:69]
	v_mfma_f32_16x16x32_bf16 v[94:97], v[150:153], v[170:173], v[94:97]
	v_mfma_f32_16x16x32_bf16 v[90:93], v[158:161], v[170:173], v[90:93]
	v_mfma_f32_16x16x32_bf16 v[86:89], v[150:153], v[174:177], v[86:89]
	v_mfma_f32_16x16x32_bf16 v[82:85], v[158:161], v[174:177], v[82:85]
	v_mfma_f32_16x16x32_bf16 v[78:81], v[150:153], v[186:189], v[78:81]
	v_mfma_f32_16x16x32_bf16 v[74:77], v[158:161], v[186:189], v[74:77]
	v_mfma_f32_16x16x32_bf16 v[70:73], v[150:153], v[190:193], v[70:73]
	v_mfma_f32_16x16x32_bf16 v[66:69], v[158:161], v[190:193], v[66:69]
	s_setprio 0
	s_barrier
	s_mov_b32 m0, s23
	ds_read_b128 v[162:165], v248 offset:16384
	ds_read_b128 v[166:169], v248 offset:18432
	ds_read_b128 v[170:173], v249 offset:16384
	ds_read_b128 v[174:177], v249 offset:18432
	ds_read_b128 v[178:181], v248 offset:20480
	ds_read_b128 v[182:185], v248 offset:22528
	ds_read_b128 v[186:189], v249 offset:20480
	ds_read_b128 v[190:193], v249 offset:22528
	buffer_load_dwordx4 v233, s[8:11], s55 offen lds
	s_mov_b32 m0, s24
	s_add_i32 s57, s55, 0x40000
	buffer_load_dwordx4 v235, s[8:11], s55 offen lds
	s_mov_b32 m0, s25
	s_nop 0
	buffer_load_dwordx4 v233, s[8:11], s57 offen lds
	s_mov_b32 m0, s27
	s_nop 0
	buffer_load_dwordx4 v235, s[8:11], s57 offen lds
	s_mov_b32 m0, s22
	s_nop 0
	buffer_load_dwordx4 v1, s[8:11], s56 offen lds
	s_mov_b32 m0, s28
	s_nop 0
	buffer_load_dwordx4 v234, s[8:11], s56 offen lds
	s_waitcnt vmcnt(8)
	s_waitcnt lgkmcnt(0)
	s_barrier
	s_setprio 1
	v_mfma_f32_16x16x32_bf16 v[62:65], v[130:133], v[162:165], v[62:65]
	v_mfma_f32_16x16x32_bf16 v[58:61], v[138:141], v[162:165], v[58:61]
	v_mfma_f32_16x16x32_bf16 v[54:57], v[130:133], v[166:169], v[54:57]
	v_mfma_f32_16x16x32_bf16 v[50:53], v[138:141], v[166:169], v[50:53]
	v_mfma_f32_16x16x32_bf16 v[46:49], v[130:133], v[178:181], v[46:49]
	v_mfma_f32_16x16x32_bf16 v[42:45], v[138:141], v[178:181], v[42:45]
	v_mfma_f32_16x16x32_bf16 v[38:41], v[130:133], v[182:185], v[38:41]
	v_mfma_f32_16x16x32_bf16 v[34:37], v[138:141], v[182:185], v[34:37]
	v_mfma_f32_16x16x32_bf16 v[62:65], v[134:137], v[170:173], v[62:65]
	v_mfma_f32_16x16x32_bf16 v[58:61], v[142:145], v[170:173], v[58:61]
	v_mfma_f32_16x16x32_bf16 v[54:57], v[134:137], v[174:177], v[54:57]
	v_mfma_f32_16x16x32_bf16 v[50:53], v[142:145], v[174:177], v[50:53]
	v_mfma_f32_16x16x32_bf16 v[46:49], v[134:137], v[186:189], v[46:49]
	v_mfma_f32_16x16x32_bf16 v[42:45], v[142:145], v[186:189], v[42:45]
	v_mfma_f32_16x16x32_bf16 v[38:41], v[134:137], v[190:193], v[38:41]
	v_mfma_f32_16x16x32_bf16 v[34:37], v[142:145], v[190:193], v[34:37]
	v_mfma_f32_16x16x32_bf16 v[30:33], v[146:149], v[162:165], v[30:33]
	v_mfma_f32_16x16x32_bf16 v[26:29], v[154:157], v[162:165], v[26:29]
	v_mfma_f32_16x16x32_bf16 v[22:25], v[146:149], v[166:169], v[22:25]
	v_mfma_f32_16x16x32_bf16 v[18:21], v[154:157], v[166:169], v[18:21]
	v_mfma_f32_16x16x32_bf16 v[14:17], v[146:149], v[178:181], v[14:17]
	v_mfma_f32_16x16x32_bf16 v[10:13], v[154:157], v[178:181], v[10:13]
	v_mfma_f32_16x16x32_bf16 v[6:9], v[146:149], v[182:185], v[6:9]
	v_mfma_f32_16x16x32_bf16 v[2:5], v[154:157], v[182:185], v[2:5]
	v_mfma_f32_16x16x32_bf16 v[30:33], v[150:153], v[170:173], v[30:33]
	v_mfma_f32_16x16x32_bf16 v[26:29], v[158:161], v[170:173], v[26:29]
	v_mfma_f32_16x16x32_bf16 v[22:25], v[150:153], v[174:177], v[22:25]
	v_mfma_f32_16x16x32_bf16 v[18:21], v[158:161], v[174:177], v[18:21]
	v_mfma_f32_16x16x32_bf16 v[14:17], v[150:153], v[186:189], v[14:17]
	v_mfma_f32_16x16x32_bf16 v[10:13], v[158:161], v[186:189], v[10:13]
	v_mfma_f32_16x16x32_bf16 v[6:9], v[150:153], v[190:193], v[6:9]
	v_mfma_f32_16x16x32_bf16 v[2:5], v[158:161], v[190:193], v[2:5]
	s_setprio 0
	s_barrier
	ds_read_b128 v[130:133], v194
	ds_read_b128 v[134:137], v195
	ds_read_b128 v[138:141], v196
	ds_read_b128 v[142:145], v197
	ds_read_b128 v[146:149], v198
	ds_read_b128 v[150:153], v199
	ds_read_b128 v[154:157], v200
	ds_read_b128 v[158:161], v201
	s_add_i32 s56, s56, 0x40000
	s_mov_b32 m0, s29
	ds_read_b128 v[162:165], v248 offset:32768
	ds_read_b128 v[166:169], v248 offset:34816
	ds_read_b128 v[170:173], v249 offset:32768
	ds_read_b128 v[174:177], v249 offset:34816
	ds_read_b128 v[178:181], v248 offset:36864
	ds_read_b128 v[182:185], v248 offset:38912
	ds_read_b128 v[186:189], v249 offset:36864
	ds_read_b128 v[190:193], v249 offset:38912
	buffer_load_dwordx4 v1, s[8:11], s56 offen lds
	s_mov_b32 m0, s30
	s_nop 0
	buffer_load_dwordx4 v234, s[8:11], s56 offen lds
	s_waitcnt vmcnt(8)
	s_waitcnt lgkmcnt(0)
	s_barrier
	s_setprio 1
	v_mfma_f32_16x16x32_bf16 v[126:129], v[130:133], v[162:165], v[126:129]
	v_mfma_f32_16x16x32_bf16 v[122:125], v[138:141], v[162:165], v[122:125]
	v_mfma_f32_16x16x32_bf16 v[118:121], v[130:133], v[166:169], v[118:121]
	v_mfma_f32_16x16x32_bf16 v[114:117], v[138:141], v[166:169], v[114:117]
	v_mfma_f32_16x16x32_bf16 v[110:113], v[130:133], v[178:181], v[110:113]
	v_mfma_f32_16x16x32_bf16 v[106:109], v[138:141], v[178:181], v[106:109]
	v_mfma_f32_16x16x32_bf16 v[102:105], v[130:133], v[182:185], v[102:105]
	v_mfma_f32_16x16x32_bf16 v[98:101], v[138:141], v[182:185], v[98:101]
	v_mfma_f32_16x16x32_bf16 v[126:129], v[134:137], v[170:173], v[126:129]
	v_mfma_f32_16x16x32_bf16 v[122:125], v[142:145], v[170:173], v[122:125]
	v_mfma_f32_16x16x32_bf16 v[118:121], v[134:137], v[174:177], v[118:121]
	v_mfma_f32_16x16x32_bf16 v[114:117], v[142:145], v[174:177], v[114:117]
	v_mfma_f32_16x16x32_bf16 v[110:113], v[134:137], v[186:189], v[110:113]
	v_mfma_f32_16x16x32_bf16 v[106:109], v[142:145], v[186:189], v[106:109]
	v_mfma_f32_16x16x32_bf16 v[102:105], v[134:137], v[190:193], v[102:105]
	v_mfma_f32_16x16x32_bf16 v[98:101], v[142:145], v[190:193], v[98:101]
	v_mfma_f32_16x16x32_bf16 v[94:97], v[146:149], v[162:165], v[94:97]
	v_mfma_f32_16x16x32_bf16 v[90:93], v[154:157], v[162:165], v[90:93]
	v_mfma_f32_16x16x32_bf16 v[86:89], v[146:149], v[166:169], v[86:89]
	v_mfma_f32_16x16x32_bf16 v[82:85], v[154:157], v[166:169], v[82:85]
	v_mfma_f32_16x16x32_bf16 v[78:81], v[146:149], v[178:181], v[78:81]
	v_mfma_f32_16x16x32_bf16 v[74:77], v[154:157], v[178:181], v[74:77]
	v_mfma_f32_16x16x32_bf16 v[70:73], v[146:149], v[182:185], v[70:73]
	v_mfma_f32_16x16x32_bf16 v[66:69], v[154:157], v[182:185], v[66:69]
	v_mfma_f32_16x16x32_bf16 v[94:97], v[150:153], v[170:173], v[94:97]
	v_mfma_f32_16x16x32_bf16 v[90:93], v[158:161], v[170:173], v[90:93]
	v_mfma_f32_16x16x32_bf16 v[86:89], v[150:153], v[174:177], v[86:89]
	v_mfma_f32_16x16x32_bf16 v[82:85], v[158:161], v[174:177], v[82:85]
	v_mfma_f32_16x16x32_bf16 v[78:81], v[150:153], v[186:189], v[78:81]
	v_mfma_f32_16x16x32_bf16 v[74:77], v[158:161], v[186:189], v[74:77]
	v_mfma_f32_16x16x32_bf16 v[70:73], v[150:153], v[190:193], v[70:73]
	v_mfma_f32_16x16x32_bf16 v[66:69], v[158:161], v[190:193], v[66:69]
	s_setprio 0
	s_barrier
	s_mov_b32 m0, s35
	s_add_i32 s56, s55, 0x80
	ds_read_b128 v[162:165], v248 offset:49152
	ds_read_b128 v[166:169], v248 offset:51200
	ds_read_b128 v[170:173], v249 offset:49152
	ds_read_b128 v[174:177], v249 offset:51200
	ds_read_b128 v[178:181], v248 offset:53248
	ds_read_b128 v[182:185], v248 offset:55296
	ds_read_b128 v[186:189], v249 offset:53248
	ds_read_b128 v[190:193], v249 offset:55296
	buffer_load_dwordx4 v233, s[8:11], s56 offen lds
	s_mov_b32 m0, s36
	s_add_i32 s55, s55, 0x40080
	buffer_load_dwordx4 v235, s[8:11], s56 offen lds
	s_mov_b32 m0, s39
	s_nop 0
	buffer_load_dwordx4 v233, s[8:11], s55 offen lds
	s_mov_b32 m0, s41
	s_nop 0
	buffer_load_dwordx4 v235, s[8:11], s55 offen lds
	s_mov_b32 m0, s37
	s_nop 0
	buffer_load_dwordx4 v1, s[8:11], s54 offen lds
	s_mov_b32 m0, s38
	s_nop 0
	buffer_load_dwordx4 v234, s[8:11], s54 offen lds
	s_waitcnt vmcnt(8)
	s_waitcnt lgkmcnt(0)
	s_barrier
	s_setprio 1
	v_mfma_f32_16x16x32_bf16 v[62:65], v[130:133], v[162:165], v[62:65]
	v_mfma_f32_16x16x32_bf16 v[58:61], v[138:141], v[162:165], v[58:61]
	v_mfma_f32_16x16x32_bf16 v[54:57], v[130:133], v[166:169], v[54:57]
	v_mfma_f32_16x16x32_bf16 v[50:53], v[138:141], v[166:169], v[50:53]
	v_mfma_f32_16x16x32_bf16 v[46:49], v[130:133], v[178:181], v[46:49]
	v_mfma_f32_16x16x32_bf16 v[42:45], v[138:141], v[178:181], v[42:45]
	v_mfma_f32_16x16x32_bf16 v[38:41], v[130:133], v[182:185], v[38:41]
	v_mfma_f32_16x16x32_bf16 v[34:37], v[138:141], v[182:185], v[34:37]
	v_mfma_f32_16x16x32_bf16 v[62:65], v[134:137], v[170:173], v[62:65]
	v_mfma_f32_16x16x32_bf16 v[58:61], v[142:145], v[170:173], v[58:61]
	v_mfma_f32_16x16x32_bf16 v[54:57], v[134:137], v[174:177], v[54:57]
	v_mfma_f32_16x16x32_bf16 v[50:53], v[142:145], v[174:177], v[50:53]
	v_mfma_f32_16x16x32_bf16 v[46:49], v[134:137], v[186:189], v[46:49]
	v_mfma_f32_16x16x32_bf16 v[42:45], v[142:145], v[186:189], v[42:45]
	v_mfma_f32_16x16x32_bf16 v[38:41], v[134:137], v[190:193], v[38:41]
	v_mfma_f32_16x16x32_bf16 v[34:37], v[142:145], v[190:193], v[34:37]
	v_mfma_f32_16x16x32_bf16 v[30:33], v[146:149], v[162:165], v[30:33]
	v_mfma_f32_16x16x32_bf16 v[26:29], v[154:157], v[162:165], v[26:29]
	v_mfma_f32_16x16x32_bf16 v[22:25], v[146:149], v[166:169], v[22:25]
	v_mfma_f32_16x16x32_bf16 v[18:21], v[154:157], v[166:169], v[18:21]
	v_mfma_f32_16x16x32_bf16 v[14:17], v[146:149], v[178:181], v[14:17]
	v_mfma_f32_16x16x32_bf16 v[10:13], v[154:157], v[178:181], v[10:13]
	v_mfma_f32_16x16x32_bf16 v[6:9], v[146:149], v[182:185], v[6:9]
	v_mfma_f32_16x16x32_bf16 v[2:5], v[154:157], v[182:185], v[2:5]
	v_mfma_f32_16x16x32_bf16 v[30:33], v[150:153], v[170:173], v[30:33]
	v_mfma_f32_16x16x32_bf16 v[26:29], v[158:161], v[170:173], v[26:29]
	v_mfma_f32_16x16x32_bf16 v[22:25], v[150:153], v[174:177], v[22:25]
	v_mfma_f32_16x16x32_bf16 v[18:21], v[158:161], v[174:177], v[18:21]
	v_mfma_f32_16x16x32_bf16 v[14:17], v[150:153], v[186:189], v[14:17]
	v_mfma_f32_16x16x32_bf16 v[10:13], v[158:161], v[186:189], v[10:13]
	v_mfma_f32_16x16x32_bf16 v[6:9], v[150:153], v[190:193], v[6:9]
	v_mfma_f32_16x16x32_bf16 v[2:5], v[158:161], v[190:193], v[2:5]
	s_setprio 0
	s_barrier
	s_add_i32 s33, s33, 2
	s_addk_i32 s53, 0x100
	s_cmp_gt_u32 s33, 13
	s_cbranch_scc0 .LBB0_1122
	s_and_b64 vcc, exec, s[16:17]
	s_cbranch_vccz .LBB0_1125
	s_barrier

.LBB0_1251:
	ds_read_b128 v[130:133], v239
	ds_read_b128 v[134:137], v240
	ds_read_b128 v[138:141], v241
	ds_read_b128 v[142:145], v242
	ds_read_b128 v[146:149], v243
	ds_read_b128 v[150:153], v244
	ds_read_b128 v[154:157], v245
	ds_read_b128 v[158:161], v246
	s_add_i32 s8, s51, s5
	s_add_i32 s31, s46, s5
	s_add_i32 s30, s8, 0x2000
	s_addk_i32 s31, 0x2000
	s_cmp_eq_u32 s5, 0
	s_cselect_b32 s33, s0, s30
	s_cselect_b32 s31, s1, s31
	s_add_i32 s30, s33, 0x80
	s_add_i32 s34, s8, 0x101f80
	s_mov_b32 s8, s70
	s_mov_b32 m0, s61
	ds_read_b128 v[162:165], v247
	ds_read_b128 v[166:169], v247 offset:2048
	ds_read_b128 v[170:173], v248
	ds_read_b128 v[174:177], v248 offset:2048
	ds_read_b128 v[178:181], v247 offset:4096
	ds_read_b128 v[182:185], v247 offset:6144
	ds_read_b128 v[186:189], v248 offset:4096
	ds_read_b128 v[190:193], v248 offset:6144
	buffer_load_dwordx4 v230, s[8:11], s34 offen lds
	s_mov_b32 m0, s64
	s_nop 0
	buffer_load_dwordx4 v233, s[8:11], s34 offen lds
	s_waitcnt vmcnt(8)
	s_waitcnt lgkmcnt(0)
	s_barrier
	s_setprio 1
	v_mfma_f32_16x16x32_bf16 v[74:77], v[130:133], v[162:165], v[74:77]
	v_mfma_f32_16x16x32_bf16 v[70:73], v[138:141], v[162:165], v[70:73]
	v_mfma_f32_16x16x32_bf16 v[66:69], v[130:133], v[166:169], v[66:69]
	v_mfma_f32_16x16x32_bf16 v[82:85], v[138:141], v[166:169], v[82:85]
	v_mfma_f32_16x16x32_bf16 v[78:81], v[130:133], v[178:181], v[78:81]
	v_mfma_f32_16x16x32_bf16 v[90:93], v[138:141], v[178:181], v[90:93]
	v_mfma_f32_16x16x32_bf16 v[86:89], v[130:133], v[182:185], v[86:89]
	v_mfma_f32_16x16x32_bf16 v[102:105], v[138:141], v[182:185], v[102:105]
	v_mfma_f32_16x16x32_bf16 v[74:77], v[134:137], v[170:173], v[74:77]
	v_mfma_f32_16x16x32_bf16 v[70:73], v[142:145], v[170:173], v[70:73]
	v_mfma_f32_16x16x32_bf16 v[66:69], v[134:137], v[174:177], v[66:69]
	v_mfma_f32_16x16x32_bf16 v[82:85], v[142:145], v[174:177], v[82:85]
	v_mfma_f32_16x16x32_bf16 v[78:81], v[134:137], v[186:189], v[78:81]
	v_mfma_f32_16x16x32_bf16 v[90:93], v[142:145], v[186:189], v[90:93]
	v_mfma_f32_16x16x32_bf16 v[86:89], v[134:137], v[190:193], v[86:89]
	v_mfma_f32_16x16x32_bf16 v[102:105], v[142:145], v[190:193], v[102:105]
	v_mfma_f32_16x16x32_bf16 v[98:101], v[146:149], v[162:165], v[98:101]
	v_mfma_f32_16x16x32_bf16 v[94:97], v[154:157], v[162:165], v[94:97]
	v_mfma_f32_16x16x32_bf16 v[106:109], v[146:149], v[166:169], v[106:109]
	v_mfma_f32_16x16x32_bf16 v[110:113], v[154:157], v[166:169], v[110:113]
	v_mfma_f32_16x16x32_bf16 v[114:117], v[146:149], v[178:181], v[114:117]
	v_mfma_f32_16x16x32_bf16 v[118:121], v[154:157], v[178:181], v[118:121]
	v_mfma_f32_16x16x32_bf16 v[122:125], v[146:149], v[182:185], v[122:125]
	v_mfma_f32_16x16x32_bf16 v[126:129], v[154:157], v[182:185], v[126:129]
	v_mfma_f32_16x16x32_bf16 v[98:101], v[150:153], v[170:173], v[98:101]
	v_mfma_f32_16x16x32_bf16 v[94:97], v[158:161], v[170:173], v[94:97]
	v_mfma_f32_16x16x32_bf16 v[106:109], v[150:153], v[174:177], v[106:109]
	v_mfma_f32_16x16x32_bf16 v[110:113], v[158:161], v[174:177], v[110:113]
	v_mfma_f32_16x16x32_bf16 v[114:117], v[150:153], v[186:189], v[114:117]
	v_mfma_f32_16x16x32_bf16 v[118:121], v[158:161], v[186:189], v[118:121]
	v_mfma_f32_16x16x32_bf16 v[122:125], v[150:153], v[190:193], v[122:125]
	v_mfma_f32_16x16x32_bf16 v[126:129], v[158:161], v[190:193], v[126:129]
	s_setprio 0
	s_barrier
	s_mov_b32 m0, s43
	ds_read_b128 v[162:165], v247 offset:16384
	ds_read_b128 v[166:169], v247 offset:18432
	ds_read_b128 v[170:173], v248 offset:16384
	ds_read_b128 v[174:177], v248 offset:18432
	ds_read_b128 v[178:181], v247 offset:20480
	ds_read_b128 v[182:185], v247 offset:22528
	ds_read_b128 v[186:189], v248 offset:20480
	ds_read_b128 v[190:193], v248 offset:22528
	buffer_load_dwordx4 v231, s[8:11], s31 offen lds
	s_mov_b32 m0, s44
	s_add_i32 s34, s31, 0x100000
	buffer_load_dwordx4 v234, s[8:11], s31 offen lds
	s_mov_b32 m0, s45
	s_nop 0
	buffer_load_dwordx4 v231, s[8:11], s34 offen lds
	s_mov_b32 m0, s47
	s_nop 0
	buffer_load_dwordx4 v234, s[8:11], s34 offen lds
	s_mov_b32 m0, s42
	s_nop 0
	buffer_load_dwordx4 v230, s[8:11], s33 offen lds
	s_mov_b32 m0, s48
	s_nop 0
	buffer_load_dwordx4 v233, s[8:11], s33 offen lds
	s_waitcnt vmcnt(8)
	s_waitcnt lgkmcnt(0)
	s_barrier
	s_setprio 1
	v_mfma_f32_16x16x32_bf16 v[10:13], v[130:133], v[162:165], v[10:13]
	v_mfma_f32_16x16x32_bf16 v[6:9], v[138:141], v[162:165], v[6:9]
	v_mfma_f32_16x16x32_bf16 v[0:3], v[130:133], v[166:169], v[2:5]
	v_mfma_f32_16x16x32_bf16 v[18:21], v[138:141], v[166:169], v[18:21]
	v_mfma_f32_16x16x32_bf16 v[14:17], v[130:133], v[178:181], v[14:17]
	v_mfma_f32_16x16x32_bf16 v[26:29], v[138:141], v[178:181], v[26:29]
	v_mfma_f32_16x16x32_bf16 v[22:25], v[130:133], v[182:185], v[22:25]
	v_mfma_f32_16x16x32_bf16 v[38:41], v[138:141], v[182:185], v[38:41]
	v_mfma_f32_16x16x32_bf16 v[10:13], v[134:137], v[170:173], v[10:13]
	v_mfma_f32_16x16x32_bf16 v[6:9], v[142:145], v[170:173], v[6:9]
	v_mfma_f32_16x16x32_bf16 v[0:3], v[134:137], v[174:177], v[0:3]
	v_mfma_f32_16x16x32_bf16 v[18:21], v[142:145], v[174:177], v[18:21]
	v_mfma_f32_16x16x32_bf16 v[14:17], v[134:137], v[186:189], v[14:17]
	v_mfma_f32_16x16x32_bf16 v[26:29], v[142:145], v[186:189], v[26:29]
	v_mfma_f32_16x16x32_bf16 v[22:25], v[134:137], v[190:193], v[22:25]
	v_mfma_f32_16x16x32_bf16 v[38:41], v[142:145], v[190:193], v[38:41]
	v_mfma_f32_16x16x32_bf16 v[34:37], v[146:149], v[162:165], v[34:37]
	v_mfma_f32_16x16x32_bf16 v[30:33], v[154:157], v[162:165], v[30:33]
	v_mfma_f32_16x16x32_bf16 v[42:45], v[146:149], v[166:169], v[42:45]
	v_mfma_f32_16x16x32_bf16 v[46:49], v[154:157], v[166:169], v[46:49]
	v_mfma_f32_16x16x32_bf16 v[50:53], v[146:149], v[178:181], v[50:53]
	v_mfma_f32_16x16x32_bf16 v[54:57], v[154:157], v[178:181], v[54:57]
	v_mfma_f32_16x16x32_bf16 v[58:61], v[146:149], v[182:185], v[58:61]
	v_mfma_f32_16x16x32_bf16 v[62:65], v[154:157], v[182:185], v[62:65]
	v_mfma_f32_16x16x32_bf16 v[34:37], v[150:153], v[170:173], v[34:37]
	v_mfma_f32_16x16x32_bf16 v[30:33], v[158:161], v[170:173], v[30:33]
	v_mfma_f32_16x16x32_bf16 v[42:45], v[150:153], v[174:177], v[42:45]
	v_mfma_f32_16x16x32_bf16 v[46:49], v[158:161], v[174:177], v[46:49]
	v_mfma_f32_16x16x32_bf16 v[50:53], v[150:153], v[186:189], v[50:53]
	v_mfma_f32_16x16x32_bf16 v[54:57], v[158:161], v[186:189], v[54:57]
	v_mfma_f32_16x16x32_bf16 v[58:61], v[150:153], v[190:193], v[58:61]
	v_mfma_f32_16x16x32_bf16 v[62:65], v[158:161], v[190:193], v[62:65]
	s_setprio 0
	s_barrier
	ds_read_b128 v[130:133], v194
	ds_read_b128 v[134:137], v195
	ds_read_b128 v[138:141], v196
	ds_read_b128 v[142:145], v197
	ds_read_b128 v[146:149], v198
	ds_read_b128 v[150:153], v199
	ds_read_b128 v[154:157], v200
	ds_read_b128 v[158:161], v201
	s_add_i32 s33, s33, 0x100000
	s_mov_b32 m0, s49
	ds_read_b128 v[162:165], v247 offset:32768
	ds_read_b128 v[166:169], v247 offset:34816
	ds_read_b128 v[170:173], v248 offset:32768
	ds_read_b128 v[174:177], v248 offset:34816
	ds_read_b128 v[178:181], v247 offset:36864
	ds_read_b128 v[182:185], v247 offset:38912
	ds_read_b128 v[186:189], v248 offset:36864
	ds_read_b128 v[190:193], v248 offset:38912
	buffer_load_dwordx4 v230, s[8:11], s33 offen lds
	s_mov_b32 m0, s50
	s_nop 0
	buffer_load_dwordx4 v233, s[8:11], s33 offen lds
	s_waitcnt vmcnt(8)
	s_waitcnt lgkmcnt(0)
	s_barrier
	s_setprio 1
	v_mfma_f32_16x16x32_bf16 v[74:77], v[130:133], v[162:165], v[74:77]
	v_mfma_f32_16x16x32_bf16 v[70:73], v[138:141], v[162:165], v[70:73]
	v_mfma_f32_16x16x32_bf16 v[66:69], v[130:133], v[166:169], v[66:69]
	v_mfma_f32_16x16x32_bf16 v[82:85], v[138:141], v[166:169], v[82:85]
	v_mfma_f32_16x16x32_bf16 v[78:81], v[130:133], v[178:181], v[78:81]
	v_mfma_f32_16x16x32_bf16 v[90:93], v[138:141], v[178:181], v[90:93]
	v_mfma_f32_16x16x32_bf16 v[86:89], v[130:133], v[182:185], v[86:89]
	v_mfma_f32_16x16x32_bf16 v[102:105], v[138:141], v[182:185], v[102:105]
	v_mfma_f32_16x16x32_bf16 v[74:77], v[134:137], v[170:173], v[74:77]
	v_mfma_f32_16x16x32_bf16 v[70:73], v[142:145], v[170:173], v[70:73]
	v_mfma_f32_16x16x32_bf16 v[66:69], v[134:137], v[174:177], v[66:69]
	v_mfma_f32_16x16x32_bf16 v[82:85], v[142:145], v[174:177], v[82:85]
	v_mfma_f32_16x16x32_bf16 v[78:81], v[134:137], v[186:189], v[78:81]
	v_mfma_f32_16x16x32_bf16 v[90:93], v[142:145], v[186:189], v[90:93]
	v_mfma_f32_16x16x32_bf16 v[86:89], v[134:137], v[190:193], v[86:89]
	v_mfma_f32_16x16x32_bf16 v[102:105], v[142:145], v[190:193], v[102:105]
	v_mfma_f32_16x16x32_bf16 v[98:101], v[146:149], v[162:165], v[98:101]
	v_mfma_f32_16x16x32_bf16 v[94:97], v[154:157], v[162:165], v[94:97]
	v_mfma_f32_16x16x32_bf16 v[106:109], v[146:149], v[166:169], v[106:109]
	v_mfma_f32_16x16x32_bf16 v[110:113], v[154:157], v[166:169], v[110:113]
	v_mfma_f32_16x16x32_bf16 v[114:117], v[146:149], v[178:181], v[114:117]
	v_mfma_f32_16x16x32_bf16 v[118:121], v[154:157], v[178:181], v[118:121]
	v_mfma_f32_16x16x32_bf16 v[122:125], v[146:149], v[182:185], v[122:125]
	v_mfma_f32_16x16x32_bf16 v[126:129], v[154:157], v[182:185], v[126:129]
	v_mfma_f32_16x16x32_bf16 v[98:101], v[150:153], v[170:173], v[98:101]
	v_mfma_f32_16x16x32_bf16 v[94:97], v[158:161], v[170:173], v[94:97]
	v_mfma_f32_16x16x32_bf16 v[106:109], v[150:153], v[174:177], v[106:109]
	v_mfma_f32_16x16x32_bf16 v[110:113], v[158:161], v[174:177], v[110:113]
	v_mfma_f32_16x16x32_bf16 v[114:117], v[150:153], v[186:189], v[114:117]
	v_mfma_f32_16x16x32_bf16 v[118:121], v[158:161], v[186:189], v[118:121]
	v_mfma_f32_16x16x32_bf16 v[122:125], v[150:153], v[190:193], v[122:125]
	v_mfma_f32_16x16x32_bf16 v[126:129], v[158:161], v[190:193], v[126:129]
	s_setprio 0
	s_barrier
	s_mov_b32 m0, s53
	s_add_i32 s33, s31, 0x80
	ds_read_b128 v[162:165], v247 offset:49152
	ds_read_b128 v[166:169], v247 offset:51200
	ds_read_b128 v[170:173], v248 offset:49152
	ds_read_b128 v[174:177], v248 offset:51200
	ds_read_b128 v[178:181], v247 offset:53248
	ds_read_b128 v[182:185], v247 offset:55296
	ds_read_b128 v[186:189], v248 offset:53248
	ds_read_b128 v[190:193], v248 offset:55296
	buffer_load_dwordx4 v231, s[8:11], s33 offen lds
	s_mov_b32 m0, s54
	s_add_i32 s31, s31, 0x100080
	buffer_load_dwordx4 v234, s[8:11], s33 offen lds
	s_mov_b32 m0, s57
	s_nop 0
	buffer_load_dwordx4 v231, s[8:11], s31 offen lds
	s_mov_b32 m0, s58
	s_nop 0
	buffer_load_dwordx4 v234, s[8:11], s31 offen lds
	s_mov_b32 m0, s55
	s_nop 0
	buffer_load_dwordx4 v230, s[8:11], s30 offen lds
	s_mov_b32 m0, s56
	s_nop 0
	buffer_load_dwordx4 v233, s[8:11], s30 offen lds
	s_waitcnt vmcnt(8)
	s_waitcnt lgkmcnt(0)
	s_barrier
	s_setprio 1
	v_mfma_f32_16x16x32_bf16 v[10:13], v[130:133], v[162:165], v[10:13]
	v_mfma_f32_16x16x32_bf16 v[4:7], v[138:141], v[162:165], v[6:9]
	v_mfma_f32_16x16x32_bf16 v[0:3], v[130:133], v[166:169], v[0:3]
	v_mfma_f32_16x16x32_bf16 v[18:21], v[138:141], v[166:169], v[18:21]
	v_mfma_f32_16x16x32_bf16 v[14:17], v[130:133], v[178:181], v[14:17]
	v_mfma_f32_16x16x32_bf16 v[26:29], v[138:141], v[178:181], v[26:29]
	v_mfma_f32_16x16x32_bf16 v[22:25], v[130:133], v[182:185], v[22:25]
	v_mfma_f32_16x16x32_bf16 v[38:41], v[138:141], v[182:185], v[38:41]
	v_mfma_f32_16x16x32_bf16 v[10:13], v[134:137], v[170:173], v[10:13]
	v_mfma_f32_16x16x32_bf16 v[6:9], v[142:145], v[170:173], v[4:7]
	v_mfma_f32_16x16x32_bf16 v[2:5], v[134:137], v[174:177], v[0:3]
	v_mfma_f32_16x16x32_bf16 v[18:21], v[142:145], v[174:177], v[18:21]
	v_mfma_f32_16x16x32_bf16 v[14:17], v[134:137], v[186:189], v[14:17]
	v_mfma_f32_16x16x32_bf16 v[26:29], v[142:145], v[186:189], v[26:29]
	v_mfma_f32_16x16x32_bf16 v[22:25], v[134:137], v[190:193], v[22:25]
	v_mfma_f32_16x16x32_bf16 v[38:41], v[142:145], v[190:193], v[38:41]
	v_mfma_f32_16x16x32_bf16 v[34:37], v[146:149], v[162:165], v[34:37]
	v_mfma_f32_16x16x32_bf16 v[30:33], v[154:157], v[162:165], v[30:33]
	v_mfma_f32_16x16x32_bf16 v[42:45], v[146:149], v[166:169], v[42:45]
	v_mfma_f32_16x16x32_bf16 v[46:49], v[154:157], v[166:169], v[46:49]
	v_mfma_f32_16x16x32_bf16 v[50:53], v[146:149], v[178:181], v[50:53]
	v_mfma_f32_16x16x32_bf16 v[54:57], v[154:157], v[178:181], v[54:57]
	v_mfma_f32_16x16x32_bf16 v[58:61], v[146:149], v[182:185], v[58:61]
	v_mfma_f32_16x16x32_bf16 v[62:65], v[154:157], v[182:185], v[62:65]
	v_mfma_f32_16x16x32_bf16 v[34:37], v[150:153], v[170:173], v[34:37]
	v_mfma_f32_16x16x32_bf16 v[30:33], v[158:161], v[170:173], v[30:33]
	v_mfma_f32_16x16x32_bf16 v[42:45], v[150:153], v[174:177], v[42:45]
	v_mfma_f32_16x16x32_bf16 v[46:49], v[158:161], v[174:177], v[46:49]
	v_mfma_f32_16x16x32_bf16 v[50:53], v[150:153], v[186:189], v[50:53]
	v_mfma_f32_16x16x32_bf16 v[54:57], v[158:161], v[186:189], v[54:57]
	v_mfma_f32_16x16x32_bf16 v[58:61], v[150:153], v[190:193], v[58:61]
	v_mfma_f32_16x16x32_bf16 v[62:65], v[158:161], v[190:193], v[62:65]
	s_setprio 0
	s_barrier
	s_add_i32 s4, s4, 2
	s_addk_i32 s5, 0x100
	s_cmp_gt_u32 s4, 61
	s_cbranch_scc0 .LBB0_1251
	s_and_b64 vcc, exec, s[18:19]
	s_cbranch_vccz .LBB0_1254
	s_barrier
